# GEMM mainloop: per-phase s_setprio flips deleted and duplicate lgkmcnt(0) waits removed (on top of the scan edits)
# speedup vs baseline: 1.0075x; 1.0075x over previous
; #define PG8_STAGE(bufoff, gbase, voff) do { _Pragma("unroll") for (int _i = 0; _i < 2; ++_i) \
;         __builtin_amdgcn_global_load_lds((const unsigned*)((const char*)(gbase) + (voff)[_i]), (LAS unsigned*)(lds + (bufoff) + ldsw + _i * 8192), 16, 0, 0); } while (0)
; #define PG8_LDA(dst, b, h) do { _Pragma("unroll") for (int m = 0; m < 4; ++m) _Pragma("unroll") for (int k = 0; k < 2; ++k) dst[m][k] = *(const LAS f16x8*)(lds + PG8_SA(b, h) + aoff + m * 2048 + k * 1024); } while (0)
; #define PG8_LDB(dst, b, h) do { _Pragma("unroll") for (int n = 0; n < 2; ++n) _Pragma("unroll") for (int k = 0; k < 2; ++k) dst[n][k] = *(const LAS f16x8*)(lds + PG8_SB(b, h) + boff + n * 2048 + k * 1024); } while (0)
; #define PG8_MMA(ai, bj, At, Bt) do { __builtin_amdgcn_s_setprio(1); _Pragma("unroll") for (int m = 0; m < 4; ++m) _Pragma("unroll") for (int n = 0; n < 2; ++n) _Pragma("unroll") for (int k = 0; k < 2; ++k) \
;         acc[ai][bj][m][n] = __builtin_amdgcn_mfma_f32_16x16x32_f16(Bt[n][k], At[m][k], acc[ai][bj][m][n], 0, 0, 0); __builtin_amdgcn_s_setprio(0); } while (0)
; #define PG8_WAIT_L(n) asm volatile("s_waitcnt lgkmcnt(" #n ")" ::: "memory")
; #define PG8_BAR __builtin_amdgcn_s_barrier()
; #define PG8_SCHED __builtin_amdgcn_sched_barrier(0)
; __device__ __forceinline__ void gemm_phase(LAS unsigned char* lds, const Job& g, const pg8::StaticOrder& S) {
;     ...
;             PG8_LDB(B0, 0, 0); PG8_SCHED; PG8_LDA(At, 0, 0); PG8_STAGE(PG8_SA(1, 1), a1 + hA, voffA);
;             PG8_WAIT_L(8); PG8_BAR; PG8_WAIT_L(0); PG8_MMA(0, 0, At, B0); PG8_BAR; PG8_SCHED;
;             PG8_LDB(B1, 0, 1); PG8_STAGE(PG8_SB(0, 0), b2, voffB);
;             PG8_BAR; PG8_WAIT_L(0); PG8_MMA(0, 1, At, B1); PG8_BAR;
;             PG8_LDA(At, 0, 1); PG8_STAGE(PG8_SA(0, 0), a2, voffA);
;             PG8_BAR; PG8_WAIT_L(0); PG8_MMA(1, 0, At, B0); PG8_BAR; PG8_SCHED;
.LBB0_182:
	s_add_i32 s44, s24, 2
	s_add_u32 s45, s10, 0x80
	s_addc_u32 s25, s11, 0
	s_add_i32 s80, 0, 0x10000
	v_add_u32_e32 v148, s80, v238
	s_waitcnt lgkmcnt(0)
	ds_read_b128 v[136:139], v148
	ds_read_b128 v[140:143], v148 offset:1024
	ds_read_b128 v[144:147], v148 offset:2048
	ds_read_b128 v[148:151], v148 offset:3072
	s_cmp_eq_u32 s97, s24
	s_cselect_b32 s24, s22, s45
	s_cselect_b32 s25, s23, s25
	s_cselect_b32 s63, s13, vcc_hi
	s_cselect_b32 s62, s12, vcc_lo
	v_lshl_add_u64 v[204:205], s[10:11], 0, v[200:201]
	s_add_i32 m0, s49, 0xc000
	ds_read_b128 v[152:155], v241
	ds_read_b128 v[156:159], v241 offset:1024
	ds_read_b128 v[160:163], v241 offset:2048
	ds_read_b128 v[164:167], v241 offset:3072
	ds_read_b128 v[168:171], v241 offset:4096
	ds_read_b128 v[172:175], v241 offset:5120
	ds_read_b128 v[176:179], v241 offset:6144
	ds_read_b128 v[180:183], v241 offset:7168
	global_load_lds_dwordx4 v[204:205], off
	v_lshl_add_u64 v[204:205], s[10:11], 0, v[202:203]
	s_add_i32 m0, s49, 0xe000
	s_nop 0
	global_load_lds_dwordx4 v[204:205], off
	s_waitcnt lgkmcnt(8)
	s_barrier
	s_waitcnt lgkmcnt(0)
	v_mfma_f32_16x16x32_f16 v[132:135], v[136:139], v[152:155], v[132:135]
	v_mfma_f32_16x16x32_f16 v[128:131], v[144:147], v[152:155], v[128:131]
	v_mfma_f32_16x16x32_f16 v[116:119], v[136:139], v[160:163], v[116:119]
	v_mfma_f32_16x16x32_f16 v[112:115], v[144:147], v[160:163], v[112:115]
	v_mfma_f32_16x16x32_f16 v[100:103], v[136:139], v[168:171], v[100:103]
	v_mfma_f32_16x16x32_f16 v[96:99], v[144:147], v[168:171], v[96:99]
	v_mfma_f32_16x16x32_f16 v[84:87], v[136:139], v[176:179], v[84:87]
	v_mfma_f32_16x16x32_f16 v[80:83], v[144:147], v[176:179], v[80:83]
	v_mfma_f32_16x16x32_f16 v[132:135], v[140:143], v[156:159], v[132:135]
	v_mfma_f32_16x16x32_f16 v[128:131], v[148:151], v[156:159], v[128:131]
	v_mfma_f32_16x16x32_f16 v[116:119], v[140:143], v[164:167], v[116:119]
	v_mfma_f32_16x16x32_f16 v[112:115], v[148:151], v[164:167], v[112:115]
	v_mfma_f32_16x16x32_f16 v[100:103], v[140:143], v[172:175], v[100:103]
	v_mfma_f32_16x16x32_f16 v[96:99], v[148:151], v[172:175], v[96:99]
	v_mfma_f32_16x16x32_f16 v[84:87], v[140:143], v[180:183], v[84:87]
	v_mfma_f32_16x16x32_f16 v[80:83], v[148:151], v[180:183], v[80:83]
	s_barrier
	s_add_i32 s45, 0, 0x14000
	s_add_i32 s80, s80, s48
	v_add_u32_e32 v216, s45, v238
	v_lshl_add_u64 v[242:243], s[62:63], 0, v[194:195]
	s_mov_b32 m0, s80
	ds_read_b128 v[204:207], v216
	ds_read_b128 v[208:211], v216 offset:1024
	ds_read_b128 v[212:215], v216 offset:2048
	ds_read_b128 v[216:219], v216 offset:3072
	global_load_lds_dwordx4 v[242:243], off
	v_lshl_add_u64 v[244:245], s[62:63], 0, v[198:199]
	s_add_i32 m0, s80, 0x2000
	s_nop 0
	global_load_lds_dwordx4 v[244:245], off
	s_barrier
	s_waitcnt lgkmcnt(0)
	v_mfma_f32_16x16x32_f16 v[124:127], v[204:207], v[152:155], v[124:127]
	v_mfma_f32_16x16x32_f16 v[120:123], v[212:215], v[152:155], v[120:123]
	v_mfma_f32_16x16x32_f16 v[108:111], v[204:207], v[160:163], v[108:111]
	v_mfma_f32_16x16x32_f16 v[104:107], v[212:215], v[160:163], v[104:107]
	v_mfma_f32_16x16x32_f16 v[92:95], v[204:207], v[168:171], v[92:95]
	v_mfma_f32_16x16x32_f16 v[88:91], v[212:215], v[168:171], v[88:91]
	v_mfma_f32_16x16x32_f16 v[76:79], v[204:207], v[176:179], v[76:79]
	v_mfma_f32_16x16x32_f16 v[72:75], v[212:215], v[176:179], v[72:75]
	v_mfma_f32_16x16x32_f16 v[124:127], v[208:211], v[156:159], v[124:127]
	v_mfma_f32_16x16x32_f16 v[120:123], v[216:219], v[156:159], v[120:123]
	v_mfma_f32_16x16x32_f16 v[108:111], v[208:211], v[164:167], v[108:111]
	v_mfma_f32_16x16x32_f16 v[104:107], v[216:219], v[164:167], v[104:107]
	v_mfma_f32_16x16x32_f16 v[92:95], v[208:211], v[172:175], v[92:95]
	v_mfma_f32_16x16x32_f16 v[88:91], v[216:219], v[172:175], v[88:91]
	v_mfma_f32_16x16x32_f16 v[76:79], v[208:211], v[180:183], v[76:79]
	v_mfma_f32_16x16x32_f16 v[72:75], v[216:219], v[180:183], v[72:75]
	s_mov_b32 m0, s49
	v_lshl_add_u64 v[246:247], s[24:25], 0, v[2:3]
	s_barrier
	ds_read_b128 v[152:155], v241 offset:16384
	ds_read_b128 v[156:159], v241 offset:17408
	ds_read_b128 v[160:163], v241 offset:18432
	ds_read_b128 v[164:167], v241 offset:19456
	ds_read_b128 v[168:171], v241 offset:20480
	ds_read_b128 v[172:175], v241 offset:21504
	ds_read_b128 v[176:179], v241 offset:22528
	ds_read_b128 v[180:183], v241 offset:23552
	global_load_lds_dwordx4 v[246:247], off
	v_lshl_add_u64 v[248:249], s[24:25], 0, v[196:197]
	s_mov_b32 m0, s51
	s_nop 0
	global_load_lds_dwordx4 v[248:249], off
	s_barrier
	s_waitcnt lgkmcnt(0)
	v_mfma_f32_16x16x32_f16 v[68:71], v[136:139], v[152:155], v[68:71]
	v_mfma_f32_16x16x32_f16 v[64:67], v[144:147], v[152:155], v[64:67]
	v_mfma_f32_16x16x32_f16 v[52:55], v[136:139], v[160:163], v[52:55]
	v_mfma_f32_16x16x32_f16 v[48:51], v[144:147], v[160:163], v[48:51]
	v_mfma_f32_16x16x32_f16 v[36:39], v[136:139], v[168:171], v[36:39]
	v_mfma_f32_16x16x32_f16 v[32:35], v[144:147], v[168:171], v[32:35]
	v_mfma_f32_16x16x32_f16 v[20:23], v[136:139], v[176:179], v[20:23]
	v_mfma_f32_16x16x32_f16 v[16:19], v[144:147], v[176:179], v[16:19]
	v_mfma_f32_16x16x32_f16 v[68:71], v[140:143], v[156:159], v[68:71]
	v_mfma_f32_16x16x32_f16 v[64:67], v[148:151], v[156:159], v[64:67]
	v_mfma_f32_16x16x32_f16 v[52:55], v[140:143], v[164:167], v[52:55]
	v_mfma_f32_16x16x32_f16 v[48:51], v[148:151], v[164:167], v[48:51]
	v_mfma_f32_16x16x32_f16 v[36:39], v[140:143], v[172:175], v[36:39]
	v_mfma_f32_16x16x32_f16 v[32:35], v[148:151], v[172:175], v[32:35]
	v_mfma_f32_16x16x32_f16 v[20:23], v[140:143], v[180:183], v[20:23]
	v_mfma_f32_16x16x32_f16 v[16:19], v[148:151], v[180:183], v[16:19]
	s_barrier
; #define PG8_STAGE(bufoff, gbase, voff) do { _Pragma("unroll") for (int _i = 0; _i < 2; ++_i) \
;         __builtin_amdgcn_global_load_lds((const unsigned*)((const char*)(gbase) + (voff)[_i]), (LAS unsigned*)(lds + (bufoff) + ldsw + _i * 8192), 16, 0, 0); } while (0)
; #define PG8_LDA(dst, b, h) do { _Pragma("unroll") for (int m = 0; m < 4; ++m) _Pragma("unroll") for (int k = 0; k < 2; ++k) dst[m][k] = *(const LAS f16x8*)(lds + PG8_SA(b, h) + aoff + m * 2048 + k * 1024); } while (0)
; #define PG8_LDB(dst, b, h) do { _Pragma("unroll") for (int n = 0; n < 2; ++n) _Pragma("unroll") for (int k = 0; k < 2; ++k) dst[n][k] = *(const LAS f16x8*)(lds + PG8_SB(b, h) + boff + n * 2048 + k * 1024); } while (0)
; #define PG8_MMA(ai, bj, At, Bt) do { __builtin_amdgcn_s_setprio(1); _Pragma("unroll") for (int m = 0; m < 4; ++m) _Pragma("unroll") for (int n = 0; n < 2; ++n) _Pragma("unroll") for (int k = 0; k < 2; ++k) \
;         acc[ai][bj][m][n] = __builtin_amdgcn_mfma_f32_16x16x32_f16(Bt[n][k], At[m][k], acc[ai][bj][m][n], 0, 0, 0); __builtin_amdgcn_s_setprio(0); } while (0)
; #define PG8_WAIT_V(n) asm volatile("s_waitcnt vmcnt(" #n ")" ::: "memory")
; #define PG8_WAIT_L(n) asm volatile("s_waitcnt lgkmcnt(" #n ")" ::: "memory")
; #define PG8_BAR __builtin_amdgcn_s_barrier()
; #define PG8_SCHED __builtin_amdgcn_sched_barrier(0)
; __device__ __forceinline__ void gemm_phase(LAS unsigned char* lds, const Job& g, const pg8::StaticOrder& S) {
;     ...
;             PG8_STAGE(PG8_SB(0, 1), b2 + hB, voffB);
;             PG8_WAIT_V(6); PG8_BAR; PG8_MMA(1, 1, At, B1); PG8_BAR;
;             PG8_LDB(B0, 1, 0); PG8_SCHED; PG8_LDA(At, 1, 0); PG8_STAGE(PG8_SA(0, 1), a2 + hA, voffA);
;             PG8_WAIT_L(8); PG8_BAR; PG8_WAIT_L(0); PG8_MMA(0, 0, At, B0); PG8_BAR; PG8_SCHED;
;             PG8_LDB(B1, 1, 1); PG8_STAGE(PG8_SB(1, 0), b3, voffB);
;             PG8_BAR; PG8_WAIT_L(0); PG8_MMA(0, 1, At, B1); PG8_BAR;
;             PG8_LDA(At, 1, 1); PG8_STAGE(PG8_SA(1, 0), a3, voffA);
	s_add_u32 s62, s62, s90
	s_addc_u32 s63, s63, s91
	s_add_i32 s45, s45, s48
	v_lshl_add_u64 v[250:251], s[62:63], 0, v[194:195]
	s_mov_b32 m0, s45
	v_lshl_add_u64 v[252:253], s[62:63], 0, v[198:199]
	global_load_lds_dwordx4 v[250:251], off
	s_add_i32 m0, s45, 0x2000
	s_nop 0
	global_load_lds_dwordx4 v[252:253], off
	s_waitcnt vmcnt(6)
	s_barrier
	v_mfma_f32_16x16x32_f16 v[60:63], v[204:207], v[152:155], v[60:63]
	v_mfma_f32_16x16x32_f16 v[56:59], v[212:215], v[152:155], v[56:59]
	v_mfma_f32_16x16x32_f16 v[44:47], v[204:207], v[160:163], v[44:47]
	v_mfma_f32_16x16x32_f16 v[40:43], v[212:215], v[160:163], v[40:43]
	v_mfma_f32_16x16x32_f16 v[28:31], v[204:207], v[168:171], v[28:31]
	v_mfma_f32_16x16x32_f16 v[24:27], v[212:215], v[168:171], v[24:27]
	v_mfma_f32_16x16x32_f16 v[12:15], v[204:207], v[176:179], v[12:15]
	v_mfma_f32_16x16x32_f16 v[8:11], v[212:215], v[176:179], v[8:11]
	v_mfma_f32_16x16x32_f16 v[60:63], v[208:211], v[156:159], v[60:63]
	v_mfma_f32_16x16x32_f16 v[56:59], v[216:219], v[156:159], v[56:59]
	v_mfma_f32_16x16x32_f16 v[44:47], v[208:211], v[164:167], v[44:47]
	v_mfma_f32_16x16x32_f16 v[40:43], v[216:219], v[164:167], v[40:43]
	v_mfma_f32_16x16x32_f16 v[28:31], v[208:211], v[172:175], v[28:31]
	v_mfma_f32_16x16x32_f16 v[24:27], v[216:219], v[172:175], v[24:27]
	v_mfma_f32_16x16x32_f16 v[12:15], v[208:211], v[180:183], v[12:15]
	v_mfma_f32_16x16x32_f16 v[8:11], v[216:219], v[180:183], v[8:11]
	s_add_i32 s45, 0, 0x18000
	v_add_u32_e32 v148, s45, v238
	s_barrier
	ds_read_b128 v[136:139], v148
	ds_read_b128 v[140:143], v148 offset:1024
	ds_read_b128 v[144:147], v148 offset:2048
	ds_read_b128 v[148:151], v148 offset:3072
	s_add_u32 s24, s24, s36
	s_addc_u32 s25, s25, s37
	s_mov_b32 m0, s3
	v_lshl_add_u64 v[204:205], s[24:25], 0, v[2:3]
	ds_read_b128 v[152:155], v241 offset:32768
	ds_read_b128 v[156:159], v241 offset:33792
	ds_read_b128 v[160:163], v241 offset:34816
	ds_read_b128 v[164:167], v241 offset:35840
	ds_read_b128 v[168:171], v241 offset:36864
	ds_read_b128 v[172:175], v241 offset:37888
	ds_read_b128 v[176:179], v241 offset:38912
	ds_read_b128 v[180:183], v241 offset:39936
	global_load_lds_dwordx4 v[204:205], off
	v_lshl_add_u64 v[204:205], s[24:25], 0, v[196:197]
	s_mov_b32 m0, s99
	s_nop 0
	global_load_lds_dwordx4 v[204:205], off
	s_waitcnt lgkmcnt(8)
	s_barrier
	s_waitcnt lgkmcnt(0)
	v_mfma_f32_16x16x32_f16 v[132:135], v[136:139], v[152:155], v[132:135]
	v_mfma_f32_16x16x32_f16 v[128:131], v[144:147], v[152:155], v[128:131]
	v_mfma_f32_16x16x32_f16 v[116:119], v[136:139], v[160:163], v[116:119]
	v_mfma_f32_16x16x32_f16 v[112:115], v[144:147], v[160:163], v[112:115]
	v_mfma_f32_16x16x32_f16 v[100:103], v[136:139], v[168:171], v[100:103]
	v_mfma_f32_16x16x32_f16 v[96:99], v[144:147], v[168:171], v[96:99]
	v_mfma_f32_16x16x32_f16 v[84:87], v[136:139], v[176:179], v[84:87]
	v_mfma_f32_16x16x32_f16 v[80:83], v[144:147], v[176:179], v[80:83]
	v_mfma_f32_16x16x32_f16 v[132:135], v[140:143], v[156:159], v[132:135]
	v_mfma_f32_16x16x32_f16 v[128:131], v[148:151], v[156:159], v[128:131]
	v_mfma_f32_16x16x32_f16 v[116:119], v[140:143], v[164:167], v[116:119]
	v_mfma_f32_16x16x32_f16 v[112:115], v[148:151], v[164:167], v[112:115]
	v_mfma_f32_16x16x32_f16 v[100:103], v[140:143], v[172:175], v[100:103]
	v_mfma_f32_16x16x32_f16 v[96:99], v[148:151], v[172:175], v[96:99]
	v_mfma_f32_16x16x32_f16 v[84:87], v[140:143], v[180:183], v[84:87]
	v_mfma_f32_16x16x32_f16 v[80:83], v[148:151], v[180:183], v[80:83]
	s_barrier
	s_add_i32 s24, 0, 0x1c000
	s_add_i32 s25, s45, s48
	v_add_u32_e32 v216, s24, v238
	v_lshl_add_u64 v[242:243], v[242:243], 0, s[76:77]
	s_mov_b32 m0, s25
	ds_read_b128 v[204:207], v216
	ds_read_b128 v[208:211], v216 offset:1024
	ds_read_b128 v[212:215], v216 offset:2048
	ds_read_b128 v[216:219], v216 offset:3072
	global_load_lds_dwordx4 v[242:243], off
	v_lshl_add_u64 v[242:243], v[244:245], 0, s[76:77]
	s_add_i32 m0, s25, 0x2000
	s_nop 0
	global_load_lds_dwordx4 v[242:243], off
	s_barrier
	s_waitcnt lgkmcnt(0)
	v_mfma_f32_16x16x32_f16 v[124:127], v[204:207], v[152:155], v[124:127]
	v_mfma_f32_16x16x32_f16 v[120:123], v[212:215], v[152:155], v[120:123]
	v_mfma_f32_16x16x32_f16 v[108:111], v[204:207], v[160:163], v[108:111]
	v_mfma_f32_16x16x32_f16 v[104:107], v[212:215], v[160:163], v[104:107]
	v_mfma_f32_16x16x32_f16 v[92:95], v[204:207], v[168:171], v[92:95]
	v_mfma_f32_16x16x32_f16 v[88:91], v[212:215], v[168:171], v[88:91]
	v_mfma_f32_16x16x32_f16 v[76:79], v[204:207], v[176:179], v[76:79]
	v_mfma_f32_16x16x32_f16 v[72:75], v[212:215], v[176:179], v[72:75]
	v_mfma_f32_16x16x32_f16 v[124:127], v[208:211], v[156:159], v[124:127]
	v_mfma_f32_16x16x32_f16 v[120:123], v[216:219], v[156:159], v[120:123]
	v_mfma_f32_16x16x32_f16 v[108:111], v[208:211], v[164:167], v[108:111]
	v_mfma_f32_16x16x32_f16 v[104:107], v[216:219], v[164:167], v[104:107]
	v_mfma_f32_16x16x32_f16 v[92:95], v[208:211], v[172:175], v[92:95]
	v_mfma_f32_16x16x32_f16 v[88:91], v[216:219], v[172:175], v[88:91]
	v_mfma_f32_16x16x32_f16 v[76:79], v[208:211], v[180:183], v[76:79]
	v_mfma_f32_16x16x32_f16 v[72:75], v[216:219], v[180:183], v[72:75]
	s_mov_b32 m0, s87
	v_lshl_add_u64 v[242:243], v[246:247], 0, s[76:77]
	s_barrier
	ds_read_b128 v[152:155], v241 offset:49152
	ds_read_b128 v[156:159], v241 offset:50176
	ds_read_b128 v[160:163], v241 offset:51200
	ds_read_b128 v[164:167], v241 offset:52224
	ds_read_b128 v[168:171], v241 offset:53248
	ds_read_b128 v[172:175], v241 offset:54272
	ds_read_b128 v[176:179], v241 offset:55296
	ds_read_b128 v[180:183], v241 offset:56320
	global_load_lds_dwordx4 v[242:243], off
	v_lshl_add_u64 v[242:243], v[248:249], 0, s[76:77]
	s_mov_b32 m0, s96
	s_nop 0
	global_load_lds_dwordx4 v[242:243], off
	s_barrier
; __device__ __forceinline__ float sigm(float x) { return __builtin_amdgcn_rcpf(1.0f + __expf(-x)); }
; #define PG8_STAGE(bufoff, gbase, voff) do { _Pragma("unroll") for (int _i = 0; _i < 2; ++_i) \
;         __builtin_amdgcn_global_load_lds((const unsigned*)((const char*)(gbase) + (voff)[_i]), (LAS unsigned*)(lds + (bufoff) + ldsw + _i * 8192), 16, 0, 0); } while (0)
; #define PG8_WAIT_V(n) asm volatile("s_waitcnt vmcnt(" #n ")" ::: "memory")
; #define PG8_BAR __builtin_amdgcn_s_barrier()
; __device__ __forceinline__ void epilogue(const Job& J, const f32x4 (&acc)[2][2][4][2], const pg8::Unit& u, int wr, int wc, int fr, int fq) {
;     ...
;     } else {
;         const int colg = u.pn * 256 + ct;
;         f32x4 bs[2][2];
; #pragma unroll
;         for (int bj = 0; bj < 2; ++bj) { bs[bj][0] = *(const f32x4*)(J.f0 + colg + bj * 128); bs[bj][1] = *(const f32x4*)(J.f0 + colg + bj * 128 + 4); }
; #pragma unroll
;         for (int ai = 0; ai < 2; ++ai)
; #pragma unroll
;             for (int mh = 0; mh < 2; ++mh) {
;                 f16x8 pl[2][2], xm[2][2];
; #pragma unroll
;                 for (int mm = 0; mm < 2; ++mm)
; #pragma unroll
;                     for (int bj = 0; bj < 2; ++bj) { const size_t o = (size_t)(row0 + ai * 128 + (mh * 2 + mm) * 16) * 2048 + colg + bj * 128;
;                         pl[mm][bj] = *(const f16x8*)(J.h0 + o); xm[mm][bj] = *(const f16x8*)(J.h1 + o); }
; #pragma unroll
;                 for (int mm = 0; mm < 2; ++mm) {
;                     const int m = mh * 2 + mm, row = row0 + ai * 128 + m * 16; float q = 0.f;
; #pragma unroll
;                     for (int bj = 0; bj < 2; ++bj) { const size_t o = (size_t)row * 2048 + colg + bj * 128;
;                         f32x4 x0, x1;
;                         const f32x4 a0 = acc[ai][bj][m][0] + bs[bj][0], a1 = acc[ai][bj][m][1] + bs[bj][1];
; #pragma unroll
;                         for (int j = 0; j < 4; ++j) { x0[j] = (float)xm[mm][bj][j] + sigm(a0[j]) * (float)pl[mm][bj][j]; x1[j] = (float)xm[mm][bj][4 + j] + sigm(a1[j]) * (float)pl[mm][bj][4 + j]; }
; __device__ __forceinline__ void gemm_phase(LAS unsigned char* lds, const Job& g, const pg8::StaticOrder& S) {
;     ...
;             PG8_BAR; PG8_WAIT_L(0); PG8_MMA(1, 0, At, B0); PG8_BAR; PG8_SCHED;
;             PG8_STAGE(PG8_SB(1, 1), b3 + hB, voffB);
;             PG8_WAIT_V(6); PG8_BAR; PG8_MMA(1, 1, At, B1); PG8_BAR;
	s_waitcnt lgkmcnt(0)
	v_mfma_f32_16x16x32_f16 v[68:71], v[136:139], v[152:155], v[68:71]
	v_mfma_f32_16x16x32_f16 v[64:67], v[144:147], v[152:155], v[64:67]
	v_mfma_f32_16x16x32_f16 v[52:55], v[136:139], v[160:163], v[52:55]
	v_mfma_f32_16x16x32_f16 v[48:51], v[144:147], v[160:163], v[48:51]
	v_mfma_f32_16x16x32_f16 v[36:39], v[136:139], v[168:171], v[36:39]
	v_mfma_f32_16x16x32_f16 v[32:35], v[144:147], v[168:171], v[32:35]
	v_mfma_f32_16x16x32_f16 v[20:23], v[136:139], v[176:179], v[20:23]
	v_mfma_f32_16x16x32_f16 v[16:19], v[144:147], v[176:179], v[16:19]
	v_mfma_f32_16x16x32_f16 v[68:71], v[140:143], v[156:159], v[68:71]
	v_mfma_f32_16x16x32_f16 v[64:67], v[148:151], v[156:159], v[64:67]
	v_mfma_f32_16x16x32_f16 v[52:55], v[140:143], v[164:167], v[52:55]
	v_mfma_f32_16x16x32_f16 v[48:51], v[148:151], v[164:167], v[48:51]
	v_mfma_f32_16x16x32_f16 v[36:39], v[140:143], v[172:175], v[36:39]
	v_mfma_f32_16x16x32_f16 v[32:35], v[148:151], v[172:175], v[32:35]
	v_mfma_f32_16x16x32_f16 v[20:23], v[140:143], v[180:183], v[20:23]
	v_mfma_f32_16x16x32_f16 v[16:19], v[148:151], v[180:183], v[16:19]
	s_barrier
	s_add_i32 s24, s24, s48
	v_lshl_add_u64 v[136:137], v[250:251], 0, s[76:77]
	s_mov_b32 m0, s24
	s_nop 0
	global_load_lds_dwordx4 v[136:137], off
	v_lshl_add_u64 v[136:137], v[252:253], 0, s[76:77]
	s_add_i32 m0, s24, 0x2000
	s_nop 0
	global_load_lds_dwordx4 v[136:137], off
	s_waitcnt vmcnt(6)
	s_barrier
	v_mfma_f32_16x16x32_f16 v[60:63], v[204:207], v[152:155], v[60:63]
	v_mfma_f32_16x16x32_f16 v[56:59], v[212:215], v[152:155], v[56:59]
	v_mfma_f32_16x16x32_f16 v[44:47], v[204:207], v[160:163], v[44:47]
	v_mfma_f32_16x16x32_f16 v[40:43], v[212:215], v[160:163], v[40:43]
	v_mfma_f32_16x16x32_f16 v[28:31], v[204:207], v[168:171], v[28:31]
	v_mfma_f32_16x16x32_f16 v[24:27], v[212:215], v[168:171], v[24:27]
	v_mfma_f32_16x16x32_f16 v[12:15], v[204:207], v[176:179], v[12:15]
	v_mfma_f32_16x16x32_f16 v[8:11], v[212:215], v[176:179], v[8:11]
	v_mfma_f32_16x16x32_f16 v[60:63], v[208:211], v[156:159], v[60:63]
	v_mfma_f32_16x16x32_f16 v[56:59], v[216:219], v[156:159], v[56:59]
	v_mfma_f32_16x16x32_f16 v[44:47], v[208:211], v[164:167], v[44:47]
	v_mfma_f32_16x16x32_f16 v[40:43], v[216:219], v[164:167], v[40:43]
	v_mfma_f32_16x16x32_f16 v[28:31], v[208:211], v[172:175], v[28:31]
	v_mfma_f32_16x16x32_f16 v[24:27], v[216:219], v[172:175], v[24:27]
	v_mfma_f32_16x16x32_f16 v[12:15], v[208:211], v[180:183], v[12:15]
	v_mfma_f32_16x16x32_f16 v[8:11], v[216:219], v[180:183], v[8:11]
	s_add_u32 s10, s10, 0x100
	s_addc_u32 s11, s11, 0
	s_add_u32 vcc_lo, vcc_lo, 0x100
	s_addc_u32 vcc_hi, vcc_hi, 0
	s_cmp_ge_u32 s44, s98
	s_mov_b32 s24, s44
	s_barrier
	s_cbranch_scc0 .LBB0_182
	v_lshl_add_u32 v204, s19, 8, v1
	s_cmp_lt_i32 s21, 2
	s_mov_b64 s[10:11], -1
	s_cbranch_scc1 .LBB0_205
	s_cmp_gt_i32 s21, 2
	s_cbranch_scc0 .LBB0_202
	v_lshl_or_b32 v206, s58, 8, v239
	v_ashrrev_i32_e32 v207, 31, v206
	v_lshl_add_u64 v[140:141], v[206:207], 2, s[56:57]
	global_load_dwordx4 v[144:147], v[140:141], off offset:16
	global_load_dwordx4 v[148:151], v[140:141], off
	global_load_dwordx4 v[136:139], v[140:141], off offset:528
	s_nop 0
	global_load_dwordx4 v[140:143], v[140:141], off offset:512
	v_and_b32_e32 v153, 64, v236
	v_xor_b32_e32 v152, 16, v236
	v_add_u32_e32 v153, 64, v153
	v_cmp_lt_i32_e32 vcc, v152, v153
	v_ashrrev_i32_e32 v205, 31, v204
	s_waitcnt vmcnt(0)
	v_add_f32_e32 v212, v132, v148
	v_cndmask_b32_e32 v152, v236, v152, vcc
	v_lshlrev_b32_e32 v243, 2, v152
	v_xor_b32_e32 v152, 32, v236
	v_cmp_lt_i32_e32 vcc, v152, v153
	v_mul_f32_e32 v212, 0xbfb8aa3b, v212
	v_exp_f32_e32 v212, v212
	v_cndmask_b32_e32 v152, v236, v152, vcc
	v_lshlrev_b32_e32 v242, 2, v152
	v_lshlrev_b64 v[152:153], 11, v[204:205]
	v_lshl_add_u64 v[152:153], v[152:153], 0, v[206:207]
	v_lshlrev_b64 v[210:211], 1, v[152:153]
	v_lshl_add_u64 v[152:153], s[66:67], 0, v[210:211]
	global_load_dwordx4 v[176:179], v[152:153], off
	v_lshl_add_u64 v[154:155], s[42:43], 0, v[210:211]
	global_load_dwordx4 v[180:183], v[154:155], off
	global_load_dwordx4 v[168:171], v[152:153], off offset:256
	global_load_dwordx4 v[172:175], v[154:155], off offset:256
	v_add_f32_e32 v212, 1.0, v212
	v_rcp_f32_e32 v218, v212
	v_add_f32_e32 v212, v128, v144
	v_mul_f32_e32 v212, 0xbfb8aa3b, v212
	v_exp_f32_e32 v212, v212
	v_or_b32_e32 v152, 16, v204
	v_ashrrev_i32_e32 v153, 31, v152
	v_lshlrev_b64 v[152:153], 11, v[152:153]
	v_lshl_add_u64 v[208:209], v[152:153], 0, v[206:207]
	v_add_f32_e32 v212, 1.0, v212
	v_lshlrev_b64 v[152:153], 1, v[208:209]
	v_rcp_f32_e32 v214, v212
	v_add_f32_e32 v212, v133, v149
	v_lshl_add_u64 v[154:155], s[66:67], 0, v[152:153]
	v_lshl_add_u64 v[156:157], s[42:43], 0, v[152:153]
	v_mul_f32_e32 v212, 0xbfb8aa3b, v212
	global_load_dwordx4 v[160:163], v[154:155], off
	global_load_dwordx4 v[164:167], v[156:157], off
	s_nop 0
	global_load_dwordx4 v[152:155], v[154:155], off offset:256
	s_nop 0
	global_load_dwordx4 v[156:159], v[156:157], off offset:256
	v_exp_f32_e32 v212, v212
	v_add_f32_e32 v213, v135, v151
	v_mul_f32_e32 v213, 0xbfb8aa3b, v213
	v_exp_f32_e32 v213, v213
	v_add_f32_e32 v212, 1.0, v212
	v_rcp_f32_e32 v219, v212
	v_add_f32_e32 v212, v129, v145
	v_mul_f32_e32 v212, 0xbfb8aa3b, v212
	v_exp_f32_e32 v212, v212
	v_add_f32_e32 v213, 1.0, v213
	v_rcp_f32_e32 v217, v213
	v_add_f32_e32 v213, v131, v147
	v_add_f32_e32 v212, 1.0, v212
	v_rcp_f32_e32 v215, v212
	v_add_f32_e32 v212, v134, v150
	v_mul_f32_e32 v212, 0xbfb8aa3b, v212
	v_exp_f32_e32 v212, v212
	v_mul_f32_e32 v213, 0xbfb8aa3b, v213
	v_exp_f32_e32 v213, v213
	v_lshl_add_u64 v[210:211], s[34:35], 0, v[210:211]
	v_add_f32_e32 v212, 1.0, v212
	v_rcp_f32_e32 v216, v212
	v_add_f32_e32 v212, v130, v146
	v_mul_f32_e32 v212, 0xbfb8aa3b, v212
	v_exp_f32_e32 v212, v212
	v_add_f32_e32 v213, 1.0, v213
	v_rcp_f32_e32 v213, v213
	v_add_f32_e32 v212, 1.0, v212
	v_rcp_f32_e32 v212, v212
	s_waitcnt vmcnt(0)
; __device__ __forceinline__ void st8acc(f16* p, const f32x4& v0, const f32x4& v1) { u32x4 w; w.x = pkh(v0[0], v0[1]); w.y = pkh(v0[2], v0[3]); w.z = pkh(v1[0], v1[1]); w.w = pkh(v1[2], v1[3]); *(u32x4*)p = w; }
; __device__ __forceinline__ float sigm(float x) { return __builtin_amdgcn_rcpf(1.0f + __expf(-x)); }
; __device__ __forceinline__ void epilogue(const Job& J, const f32x4 (&acc)[2][2][4][2], const pg8::Unit& u, int wr, int wc, int fr, int fq) {
;     ...
;                 for (int mm = 0; mm < 2; ++mm) {
;                     const int m = mh * 2 + mm, row = row0 + ai * 128 + m * 16; float q = 0.f;
; #pragma unroll
;                     for (int bj = 0; bj < 2; ++bj) { const size_t o = (size_t)row * 2048 + colg + bj * 128;
;                         f32x4 x0, x1;
;                         const f32x4 a0 = acc[ai][bj][m][0] + bs[bj][0], a1 = acc[ai][bj][m][1] + bs[bj][1];
; #pragma unroll
;                         for (int j = 0; j < 4; ++j) { x0[j] = (float)xm[mm][bj][j] + sigm(a0[j]) * (float)pl[mm][bj][j]; x1[j] = (float)xm[mm][bj][4 + j] + sigm(a1[j]) * (float)pl[mm][bj][4 + j]; }
;                         if (J.o32) { *(f32x4*)(J.o32 + o) = x0; *(f32x4*)(J.o32 + o + 4) = x1; } else st8acc(J.o16 + o, x0, x1);
;                         q += ((x0[0] * x0[0] + x0[1] * x0[1]) + (x0[2] * x0[2] + x0[3] * x0[3])) + ((x1[0] * x1[0] + x1[1] * x1[1]) + (x1[2] * x1[2] + x1[3] * x1[3])); }
;                     q += __shfl_xor(q, 16); q += __shfl_xor(q, 32);
;                     if (fq == 0) atomicAdd(J.xsq + row, q);
	v_cvt_f32_f16_e32 v244, v180
	v_cvt_f32_f16_sdwa v245, v180 dst_sel:DWORD dst_unused:UNUSED_PAD src0_sel:WORD_1
	v_cvt_f32_f16_e32 v246, v176
	v_cvt_f32_f16_sdwa v247, v176 dst_sel:DWORD dst_unused:UNUSED_PAD src0_sel:WORD_1
	v_cvt_f32_f16_e32 v180, v181
	v_cvt_f32_f16_sdwa v181, v181 dst_sel:DWORD dst_unused:UNUSED_PAD src0_sel:WORD_1
	v_pk_fma_f32 v[218:219], v[218:219], v[246:247], v[244:245]
	v_cvt_f32_f16_e32 v244, v177
	v_cvt_f32_f16_sdwa v245, v177 dst_sel:DWORD dst_unused:UNUSED_PAD src0_sel:WORD_1
	v_cvt_pk_f16_f32 v176, v218, v219
	v_cvt_f32_f16_e32 v246, v168
	v_cvt_f32_f16_sdwa v247, v168 dst_sel:DWORD dst_unused:UNUSED_PAD src0_sel:WORD_1
	v_pk_fma_f32 v[180:181], v[216:217], v[244:245], v[180:181]
	v_cvt_f32_f16_e32 v216, v182
	v_cvt_f32_f16_sdwa v217, v182 dst_sel:DWORD dst_unused:UNUSED_PAD src0_sel:WORD_1
	v_cvt_f32_f16_e32 v244, v178
	v_cvt_f32_f16_sdwa v245, v178 dst_sel:DWORD dst_unused:UNUSED_PAD src0_sel:WORD_1
	v_cvt_f32_f16_e32 v182, v183
	v_cvt_f32_f16_sdwa v183, v183 dst_sel:DWORD dst_unused:UNUSED_PAD src0_sel:WORD_1
	v_cvt_pk_f16_f32 v177, v180, v181
	v_pk_fma_f32 v[214:215], v[214:215], v[244:245], v[216:217]
	v_cvt_f32_f16_e32 v216, v179
	v_cvt_f32_f16_sdwa v217, v179 dst_sel:DWORD dst_unused:UNUSED_PAD src0_sel:WORD_1
	v_cvt_pk_f16_f32 v178, v214, v215
	v_cvt_f32_f16_e32 v244, v172
	v_cvt_f32_f16_sdwa v245, v172 dst_sel:DWORD dst_unused:UNUSED_PAD src0_sel:WORD_1
	v_pk_fma_f32 v[182:183], v[212:213], v[216:217], v[182:183]
	v_add_f32_e32 v213, v120, v136
	v_mul_f32_e32 v213, 0xbfb8aa3b, v213
	v_exp_f32_e32 v213, v213
	v_add_f32_e32 v217, v122, v138
	v_mul_f32_e32 v217, 0xbfb8aa3b, v217
	v_cvt_pk_f16_f32 v179, v182, v183
	v_add_f32_e32 v213, 1.0, v213
	v_exp_f32_e32 v217, v217
	global_store_dwordx4 v[210:211], v[176:179], off
	v_add_f32_e32 v212, v124, v140
	v_mul_f32_e32 v212, 0xbfb8aa3b, v212
	v_pk_mul_f32 v[178:179], v[180:181], v[180:181]
	v_pk_mul_f32 v[180:181], v[214:215], v[214:215]
	v_rcp_f32_e32 v214, v213
	v_add_f32_e32 v213, v125, v141
	v_mul_f32_e32 v213, 0xbfb8aa3b, v213
	v_exp_f32_e32 v212, v212
	v_exp_f32_e32 v213, v213
	v_add_f32_e32 v217, 1.0, v217
	v_pk_mul_f32 v[176:177], v[218:219], v[218:219]
	v_add_f32_e32 v216, v126, v142
	v_rcp_f32_e32 v218, v217
	v_add_f32_e32 v217, v127, v143
	v_mul_f32_e32 v216, 0xbfb8aa3b, v216
	v_mul_f32_e32 v217, 0xbfb8aa3b, v217
	v_add_f32_e32 v212, 1.0, v212
	v_add_f32_e32 v213, 1.0, v213
	v_exp_f32_e32 v216, v216
	v_exp_f32_e32 v217, v217
	v_rcp_f32_e32 v212, v212
	v_rcp_f32_e32 v213, v213
	v_add_f32_e32 v215, v121, v137
	v_mul_f32_e32 v215, 0xbfb8aa3b, v215
	v_exp_f32_e32 v215, v215
	v_add_f32_e32 v216, 1.0, v216
	v_add_f32_e32 v217, 1.0, v217
	v_rcp_f32_e32 v216, v216
	v_rcp_f32_e32 v217, v217
	v_pk_fma_f32 v[212:213], v[212:213], v[246:247], v[244:245]
	v_cvt_f32_f16_e32 v172, v173
	v_cvt_f32_f16_sdwa v173, v173 dst_sel:DWORD dst_unused:UNUSED_PAD src0_sel:WORD_1
	v_cvt_f32_f16_e32 v244, v169
	v_cvt_f32_f16_sdwa v245, v169 dst_sel:DWORD dst_unused:UNUSED_PAD src0_sel:WORD_1
	v_add_f32_e32 v219, v123, v139
	v_mul_f32_e32 v219, 0xbfb8aa3b, v219
	v_add_f32_e32 v215, 1.0, v215
	v_exp_f32_e32 v219, v219
	v_rcp_f32_e32 v215, v215
	v_pk_fma_f32 v[172:173], v[216:217], v[244:245], v[172:173]
	v_cvt_f32_f16_e32 v216, v174
	v_cvt_f32_f16_sdwa v217, v174 dst_sel:DWORD dst_unused:UNUSED_PAD src0_sel:WORD_1
	v_cvt_f32_f16_e32 v244, v170
	v_cvt_f32_f16_sdwa v245, v170 dst_sel:DWORD dst_unused:UNUSED_PAD src0_sel:WORD_1
	v_add_f32_e32 v219, 1.0, v219
	v_rcp_f32_e32 v219, v219
	v_cvt_f32_f16_e32 v174, v175
	v_pk_fma_f32 v[214:215], v[214:215], v[244:245], v[216:217]
	v_cvt_f32_f16_sdwa v175, v175 dst_sel:DWORD dst_unused:UNUSED_PAD src0_sel:WORD_1
	v_cvt_f32_f16_e32 v216, v171
	v_cvt_f32_f16_sdwa v217, v171 dst_sel:DWORD dst_unused:UNUSED_PAD src0_sel:WORD_1
	v_cvt_pk_f16_f32 v168, v212, v213
	v_cvt_pk_f16_f32 v169, v172, v173
	v_cvt_pk_f16_f32 v170, v214, v215
	v_pk_fma_f32 v[174:175], v[218:219], v[216:217], v[174:175]
	v_pk_mul_f32 v[182:183], v[182:183], v[182:183]
	v_cvt_pk_f16_f32 v171, v174, v175
	global_store_dwordx4 v[210:211], v[168:171], off offset:256
	v_pk_mul_f32 v[174:175], v[174:175], v[174:175]
	s_nop 0
	v_pk_mul_f32 v[168:169], v[212:213], v[212:213]
	v_pk_mul_f32 v[170:171], v[172:173], v[172:173]
	v_add_f32_e32 v168, v168, v169
	v_add_f32_e32 v170, v170, v171
	v_pk_mul_f32 v[172:173], v[214:215], v[214:215]
	v_add_f32_e32 v168, v168, v170
	v_add_f32_e32 v169, v182, v183
	v_add_f32_e32 v170, v180, v181
	v_add_f32_e32 v174, v174, v175
	v_add_f32_e32 v172, v172, v173
	v_add_f32_e32 v169, v170, v169
	v_add_f32_e32 v170, v178, v179
	v_add_f32_e32 v171, v176, v177
	v_add_f32_e32 v172, v172, v174
	v_add_f32_e32 v170, v171, v170
	v_add_f32_e32 v168, v168, v172
	v_add_f32_e32 v169, v170, v169
	v_add_f32_e32 v168, v169, v168
	ds_bpermute_b32 v169, v243, v168
	v_lshl_add_u64 v[180:181], v[204:205], 2, s[60:61]
	s_waitcnt lgkmcnt(0)
	v_add_f32_e32 v168, v168, v169
	ds_bpermute_b32 v169, v242, v168
	s_and_saveexec_b64 s[10:11], s[4:5]
	s_cbranch_execz .LBB0_187
	s_waitcnt lgkmcnt(0)
	v_add_f32_e32 v168, v168, v169
	global_atomic_add_f32 v[180:181], v168, off

; #define PG8_WAIT_V(n) asm volatile("s_waitcnt vmcnt(" #n ")" ::: "memory")
; #define PG8_BAR __builtin_amdgcn_s_barrier()
; __device__ __forceinline__ void gemm_phase(LAS unsigned char* lds, const Job& g, const pg8::StaticOrder& S) {
;     ...
;     PG8_WAIT_V(0);
;     if (wr == 0) PG8_BAR;
;     PG8_BAR;
.LBB0_244:
	s_setprio 0
	s_waitcnt vmcnt(0)
	s_cmpk_gt_u32 s47, 0xff
	s_mov_b64 s[84:85], 0x800
	s_cbranch_scc1 .LBB0_141
	s_barrier
	s_branch .LBB0_141
